# P2 residual epilogue de-serialised: 8 residual loads in flight with counted vmcnt instead of load-wait-fma-store ladder
# baseline (speedup 1.0000x reference)
.LBB0_250:
	v_lshl_add_u32 v152, s52, 8, v142
	v_lshl_or_b32 v154, s53, 8, v144
	v_ashrrev_i32_e32 v153, 31, v152
	v_ashrrev_i32_e32 v155, 31, v154
	v_lshlrev_b64 v[140:141], 10, v[152:153]
	v_lshl_add_u64 v[140:141], v[140:141], 0, v[154:155]
	v_lshlrev_b64 v[140:141], 2, v[140:141]
	s_and_b64 vcc, exec, s[2:3]
	s_mov_b64 s[2:3], -1
	v_add_u32_e32 v200, 0x10000, v140
	v_add_u32_e32 v201, 0x20000, v140
	v_add_u32_e32 v202, 0x30000, v140
	v_add_u32_e32 v203, 0x80000, v140
	v_add_u32_e32 v204, 0x90000, v140
	v_add_u32_e32 v205, 0xa0000, v140
	v_add_u32_e32 v206, 0xb0000, v140
	global_load_dwordx4 v[160:163], v140, s[6:7]
	global_load_dwordx4 v[164:167], v140, s[6:7] offset:64
	global_load_dwordx4 v[168:171], v140, s[6:7] offset:512
	global_load_dwordx4 v[172:175], v140, s[6:7] offset:576
	global_load_dwordx4 v[176:179], v200, s[6:7]
	global_load_dwordx4 v[180:183], v200, s[6:7] offset:64
	global_load_dwordx4 v[184:187], v200, s[6:7] offset:512
	global_load_dwordx4 v[188:191], v200, s[6:7] offset:576
	s_waitcnt vmcnt(7)
	v_pk_fma_f32 v[162:163], v[126:127], 0.5, v[162:163] op_sel_hi:[1,0,1]
	v_pk_fma_f32 v[160:161], v[124:125], 0.5, v[160:161] op_sel_hi:[1,0,1]
	global_store_dwordx4 v140, v[160:163], s[8:9]
	global_load_dwordx4 v[192:195], v201, s[6:7]
	s_waitcnt vmcnt(8)
	v_pk_fma_f32 v[166:167], v[122:123], 0.5, v[166:167] op_sel_hi:[1,0,1]
	v_pk_fma_f32 v[164:165], v[120:121], 0.5, v[164:165] op_sel_hi:[1,0,1]
	global_store_dwordx4 v140, v[164:167], s[8:9] offset:64
	global_load_dwordx4 v[196:199], v201, s[6:7] offset:64
	s_waitcnt vmcnt(9)
	v_pk_fma_f32 v[170:171], v[118:119], 0.5, v[170:171] op_sel_hi:[1,0,1]
	v_pk_fma_f32 v[168:169], v[116:117], 0.5, v[168:169] op_sel_hi:[1,0,1]
	global_store_dwordx4 v140, v[168:171], s[8:9] offset:512
	global_load_dwordx4 v[160:163], v201, s[6:7] offset:512
	s_waitcnt vmcnt(10)
	v_pk_fma_f32 v[174:175], v[106:107], 0.5, v[174:175] op_sel_hi:[1,0,1]
	v_pk_fma_f32 v[172:173], v[104:105], 0.5, v[172:173] op_sel_hi:[1,0,1]
	global_store_dwordx4 v140, v[172:175], s[8:9] offset:576
	global_load_dwordx4 v[164:167], v201, s[6:7] offset:576
	s_waitcnt vmcnt(11)
	v_pk_fma_f32 v[178:179], v[114:115], 0.5, v[178:179] op_sel_hi:[1,0,1]
	v_pk_fma_f32 v[176:177], v[112:113], 0.5, v[176:177] op_sel_hi:[1,0,1]
	global_store_dwordx4 v200, v[176:179], s[8:9]
	global_load_dwordx4 v[168:171], v202, s[6:7]
	s_waitcnt vmcnt(12)
	v_pk_fma_f32 v[182:183], v[110:111], 0.5, v[182:183] op_sel_hi:[1,0,1]
	v_pk_fma_f32 v[180:181], v[108:109], 0.5, v[180:181] op_sel_hi:[1,0,1]
	global_store_dwordx4 v200, v[180:183], s[8:9] offset:64
	global_load_dwordx4 v[172:175], v202, s[6:7] offset:64
	s_waitcnt vmcnt(13)
	v_pk_fma_f32 v[186:187], v[102:103], 0.5, v[186:187] op_sel_hi:[1,0,1]
	v_pk_fma_f32 v[184:185], v[100:101], 0.5, v[184:185] op_sel_hi:[1,0,1]
	global_store_dwordx4 v200, v[184:187], s[8:9] offset:512
	global_load_dwordx4 v[176:179], v202, s[6:7] offset:512
	s_waitcnt vmcnt(14)
	v_pk_fma_f32 v[190:191], v[90:91], 0.5, v[190:191] op_sel_hi:[1,0,1]
	v_pk_fma_f32 v[188:189], v[88:89], 0.5, v[188:189] op_sel_hi:[1,0,1]
	global_store_dwordx4 v200, v[188:191], s[8:9] offset:576
	global_load_dwordx4 v[180:183], v202, s[6:7] offset:576
	s_waitcnt vmcnt(14)
	v_pk_fma_f32 v[194:195], v[98:99], 0.5, v[194:195] op_sel_hi:[1,0,1]
	v_pk_fma_f32 v[192:193], v[96:97], 0.5, v[192:193] op_sel_hi:[1,0,1]
	global_store_dwordx4 v201, v[192:195], s[8:9]
	global_load_dwordx4 v[184:187], v203, s[6:7]
	s_waitcnt vmcnt(14)
	v_pk_fma_f32 v[198:199], v[94:95], 0.5, v[198:199] op_sel_hi:[1,0,1]
	v_pk_fma_f32 v[196:197], v[92:93], 0.5, v[196:197] op_sel_hi:[1,0,1]
	global_store_dwordx4 v201, v[196:199], s[8:9] offset:64
	global_load_dwordx4 v[188:191], v203, s[6:7] offset:64
	s_waitcnt vmcnt(14)
	v_pk_fma_f32 v[162:163], v[86:87], 0.5, v[162:163] op_sel_hi:[1,0,1]
	v_pk_fma_f32 v[160:161], v[84:85], 0.5, v[160:161] op_sel_hi:[1,0,1]
	global_store_dwordx4 v201, v[160:163], s[8:9] offset:512
	global_load_dwordx4 v[192:195], v203, s[6:7] offset:512
	s_waitcnt vmcnt(14)
	v_pk_fma_f32 v[166:167], v[74:75], 0.5, v[166:167] op_sel_hi:[1,0,1]
	v_pk_fma_f32 v[164:165], v[72:73], 0.5, v[164:165] op_sel_hi:[1,0,1]
	global_store_dwordx4 v201, v[164:167], s[8:9] offset:576
	global_load_dwordx4 v[196:199], v203, s[6:7] offset:576
	s_waitcnt vmcnt(14)
	v_pk_fma_f32 v[170:171], v[82:83], 0.5, v[170:171] op_sel_hi:[1,0,1]
	v_pk_fma_f32 v[168:169], v[80:81], 0.5, v[168:169] op_sel_hi:[1,0,1]
	global_store_dwordx4 v202, v[168:171], s[8:9]
	global_load_dwordx4 v[160:163], v204, s[6:7]
	s_waitcnt vmcnt(14)
	v_pk_fma_f32 v[174:175], v[78:79], 0.5, v[174:175] op_sel_hi:[1,0,1]
	v_pk_fma_f32 v[172:173], v[76:77], 0.5, v[172:173] op_sel_hi:[1,0,1]
	global_store_dwordx4 v202, v[172:175], s[8:9] offset:64
	global_load_dwordx4 v[164:167], v204, s[6:7] offset:64
	s_waitcnt vmcnt(14)
	v_pk_fma_f32 v[178:179], v[70:71], 0.5, v[178:179] op_sel_hi:[1,0,1]
	v_pk_fma_f32 v[176:177], v[68:69], 0.5, v[176:177] op_sel_hi:[1,0,1]
	global_store_dwordx4 v202, v[176:179], s[8:9] offset:512
	global_load_dwordx4 v[168:171], v204, s[6:7] offset:512
	s_waitcnt vmcnt(14)
	v_pk_fma_f32 v[182:183], v[66:67], 0.5, v[182:183] op_sel_hi:[1,0,1]
	v_pk_fma_f32 v[180:181], v[64:65], 0.5, v[180:181] op_sel_hi:[1,0,1]
	global_store_dwordx4 v202, v[180:183], s[8:9] offset:576
	global_load_dwordx4 v[172:175], v204, s[6:7] offset:576
	s_waitcnt vmcnt(14)
	v_pk_fma_f32 v[186:187], v[62:63], 0.5, v[186:187] op_sel_hi:[1,0,1]
	v_pk_fma_f32 v[184:185], v[60:61], 0.5, v[184:185] op_sel_hi:[1,0,1]
	global_store_dwordx4 v203, v[184:187], s[8:9]
	global_load_dwordx4 v[176:179], v205, s[6:7]
	s_waitcnt vmcnt(14)
	v_pk_fma_f32 v[190:191], v[58:59], 0.5, v[190:191] op_sel_hi:[1,0,1]
	v_pk_fma_f32 v[188:189], v[56:57], 0.5, v[188:189] op_sel_hi:[1,0,1]
	global_store_dwordx4 v203, v[188:191], s[8:9] offset:64
	global_load_dwordx4 v[180:183], v205, s[6:7] offset:64
	s_waitcnt vmcnt(14)
	v_pk_fma_f32 v[194:195], v[54:55], 0.5, v[194:195] op_sel_hi:[1,0,1]
	v_pk_fma_f32 v[192:193], v[52:53], 0.5, v[192:193] op_sel_hi:[1,0,1]
	global_store_dwordx4 v203, v[192:195], s[8:9] offset:512
	global_load_dwordx4 v[184:187], v205, s[6:7] offset:512
	s_waitcnt vmcnt(14)
	v_pk_fma_f32 v[198:199], v[42:43], 0.5, v[198:199] op_sel_hi:[1,0,1]
	v_pk_fma_f32 v[196:197], v[40:41], 0.5, v[196:197] op_sel_hi:[1,0,1]
	global_store_dwordx4 v203, v[196:199], s[8:9] offset:576
	global_load_dwordx4 v[188:191], v205, s[6:7] offset:576
	s_waitcnt vmcnt(14)
	v_pk_fma_f32 v[162:163], v[50:51], 0.5, v[162:163] op_sel_hi:[1,0,1]
	v_pk_fma_f32 v[160:161], v[48:49], 0.5, v[160:161] op_sel_hi:[1,0,1]
	global_store_dwordx4 v204, v[160:163], s[8:9]
	global_load_dwordx4 v[192:195], v206, s[6:7]
	s_waitcnt vmcnt(14)
	v_pk_fma_f32 v[166:167], v[46:47], 0.5, v[166:167] op_sel_hi:[1,0,1]
	v_pk_fma_f32 v[164:165], v[44:45], 0.5, v[164:165] op_sel_hi:[1,0,1]
	global_store_dwordx4 v204, v[164:167], s[8:9] offset:64
	global_load_dwordx4 v[196:199], v206, s[6:7] offset:64
	s_waitcnt vmcnt(14)
	v_pk_fma_f32 v[170:171], v[38:39], 0.5, v[170:171] op_sel_hi:[1,0,1]
	v_pk_fma_f32 v[168:169], v[36:37], 0.5, v[168:169] op_sel_hi:[1,0,1]
	global_store_dwordx4 v204, v[168:171], s[8:9] offset:512
	global_load_dwordx4 v[160:163], v206, s[6:7] offset:512
	s_waitcnt vmcnt(14)
	v_pk_fma_f32 v[174:175], v[26:27], 0.5, v[174:175] op_sel_hi:[1,0,1]
	v_pk_fma_f32 v[172:173], v[24:25], 0.5, v[172:173] op_sel_hi:[1,0,1]
	global_store_dwordx4 v204, v[172:175], s[8:9] offset:576
	global_load_dwordx4 v[164:167], v206, s[6:7] offset:576
	s_waitcnt vmcnt(14)
	v_pk_fma_f32 v[178:179], v[34:35], 0.5, v[178:179] op_sel_hi:[1,0,1]
	v_pk_fma_f32 v[176:177], v[32:33], 0.5, v[176:177] op_sel_hi:[1,0,1]
	global_store_dwordx4 v205, v[176:179], s[8:9]
	s_waitcnt vmcnt(13)
	v_pk_fma_f32 v[182:183], v[30:31], 0.5, v[182:183] op_sel_hi:[1,0,1]
	v_pk_fma_f32 v[180:181], v[28:29], 0.5, v[180:181] op_sel_hi:[1,0,1]
	global_store_dwordx4 v205, v[180:183], s[8:9] offset:64
	s_waitcnt vmcnt(12)
	v_pk_fma_f32 v[186:187], v[22:23], 0.5, v[186:187] op_sel_hi:[1,0,1]
	v_pk_fma_f32 v[184:185], v[20:21], 0.5, v[184:185] op_sel_hi:[1,0,1]
	global_store_dwordx4 v205, v[184:187], s[8:9] offset:512
	s_waitcnt vmcnt(11)
	v_pk_fma_f32 v[190:191], v[10:11], 0.5, v[190:191] op_sel_hi:[1,0,1]
	v_pk_fma_f32 v[188:189], v[8:9], 0.5, v[188:189] op_sel_hi:[1,0,1]
	global_store_dwordx4 v205, v[188:191], s[8:9] offset:576
	s_waitcnt vmcnt(10)
	v_pk_fma_f32 v[194:195], v[18:19], 0.5, v[194:195] op_sel_hi:[1,0,1]
	v_pk_fma_f32 v[192:193], v[16:17], 0.5, v[192:193] op_sel_hi:[1,0,1]
	global_store_dwordx4 v206, v[192:195], s[8:9]
	s_waitcnt vmcnt(9)
	v_pk_fma_f32 v[198:199], v[14:15], 0.5, v[198:199] op_sel_hi:[1,0,1]
	v_pk_fma_f32 v[196:197], v[12:13], 0.5, v[196:197] op_sel_hi:[1,0,1]
	global_store_dwordx4 v206, v[196:199], s[8:9] offset:64
	s_waitcnt vmcnt(8)
	v_pk_fma_f32 v[162:163], v[6:7], 0.5, v[162:163] op_sel_hi:[1,0,1]
	v_pk_fma_f32 v[160:161], v[4:5], 0.5, v[160:161] op_sel_hi:[1,0,1]
	global_store_dwordx4 v206, v[160:163], s[8:9] offset:512
	s_waitcnt vmcnt(7)
	v_pk_fma_f32 v[166:167], v[2:3], 0.5, v[166:167] op_sel_hi:[1,0,1]
	v_pk_fma_f32 v[164:165], v[0:1], 0.5, v[164:165] op_sel_hi:[1,0,1]
	global_store_dwordx4 v206, v[164:167], s[8:9] offset:576
	s_cbranch_vccnz .LBB0_235
	s_andn2_b64 vcc, exec, s[12:13]
	s_cbranch_vccnz .LBB0_234
	s_barrier
	s_branch .LBB0_234
